# FoX lazy tiles: rescale threshold raised from 8 to 24 log2 units (fewer fall-backs under the monotone decay bias)
# baseline (speedup 1.0000x reference)
.Lfoxf_lazy:
	v_min3_f32 v240, v186, v185, v167
	v_min_f32_e32 v240, v240, v166
	v_cmp_gt_f32_e32 vcc, 0xefa18f08, v240
	s_nop 1
	s_cbranch_vccnz .Lfoxf_fast
	s_lshl_b32 s84, s23, 6
	v_lshl_add_u64 v[158:159], s[84:85], 2, v[146:147]
	global_load_dwordx4 v[224:227], v[158:159], off
	global_load_dwordx4 v[228:231], v[158:159], off offset:64
	global_load_dwordx4 v[232:235], v[158:159], off offset:128
	global_load_dwordx4 v[236:239], v[158:159], off offset:192
	s_lshl_b32 s4, s21, 14
	v_or_b32_e32 v193, s4, v178
	v_add_u32_e32 v248, v193, v176
	v_add_u32_e32 v249, v193, v177
	v_add_u32_e32 v191, v175, v176
	v_add_u32_e32 v192, v175, v177
	v_add_u32_e32 v187, v193, v181
	v_add_u32_e32 v188, v193, v182
	v_add_u32_e32 v189, v193, v183
	v_add_u32_e32 v190, v193, v184
	ds_read_b128 v[64:67], v248
	ds_read_b128 v[68:71], v248 offset:2048
	ds_read_b128 v[72:75], v249
	ds_read_b128 v[76:79], v249 offset:2048
	ds_read_b128 v[96:99], v191 offset:32768
	ds_read_b128 v[100:103], v192 offset:32768
	ds_read_b128 v[104:107], v191 offset:34816
	ds_read_b128 v[108:111], v192 offset:34816
	ds_read_b64 v[80:81], v187 offset:8192
	ds_read_b64 v[82:83], v188 offset:8192
	ds_read_b64 v[84:85], v187 offset:10240
	ds_read_b64 v[86:87], v188 offset:10240
	ds_read_b64 v[88:89], v187 offset:12288
	ds_read_b64 v[90:91], v188 offset:12288
	ds_read_b64 v[92:93], v187 offset:14336
	ds_read_b64 v[94:95], v188 offset:14336
	v_sub_f32_e32 v244, v131, v186
	v_sub_f32_e32 v245, v155, v185
	v_sub_f32_e32 v246, v168, v167
	v_sub_f32_e32 v247, v169, v166
	s_waitcnt vmcnt(2)
	s_waitcnt lgkmcnt(8)
	v_sub_f32_e32 v112, v244, v224
	v_sub_f32_e32 v113, v244, v225
	v_sub_f32_e32 v114, v244, v226
	v_sub_f32_e32 v115, v244, v227
	v_sub_f32_e32 v116, v244, v228
	v_sub_f32_e32 v117, v244, v229
	v_sub_f32_e32 v118, v244, v230
	v_sub_f32_e32 v119, v244, v231
	v_mfma_f32_16x16x32_bf16 v[112:115], v[64:67], v[96:99], v[112:115]
	v_sub_f32_e32 v120, v245, v224
	v_sub_f32_e32 v121, v245, v225
	v_sub_f32_e32 v122, v245, v226
	v_sub_f32_e32 v123, v245, v227
	v_mfma_f32_16x16x32_bf16 v[116:119], v[68:71], v[96:99], v[116:119]
	v_sub_f32_e32 v124, v245, v228
	v_sub_f32_e32 v125, v245, v229
	v_sub_f32_e32 v126, v245, v230
	v_sub_f32_e32 v127, v245, v231
	v_mfma_f32_16x16x32_bf16 v[120:123], v[64:67], v[104:107], v[120:123]
	v_mfma_f32_16x16x32_bf16 v[112:115], v[72:75], v[100:103], v[112:115]
	v_mfma_f32_16x16x32_bf16 v[124:127], v[68:71], v[104:107], v[124:127]
	v_mfma_f32_16x16x32_bf16 v[116:119], v[76:79], v[100:103], v[116:119]
	v_mfma_f32_16x16x32_bf16 v[120:123], v[72:75], v[108:111], v[120:123]
	v_mfma_f32_16x16x32_bf16 v[124:127], v[76:79], v[108:111], v[124:127]
	ds_read_b128 v[96:99], v191 offset:36864
	ds_read_b128 v[100:103], v192 offset:36864
	ds_read_b128 v[104:107], v191 offset:38912
	ds_read_b128 v[108:111], v192 offset:38912
	s_nop 0
	v_max3_f32 v240, v112, v113, v114
	v_max3_f32 v240, v240, v115, v116
	v_max3_f32 v240, v240, v117, v118
	v_max_f32_e32 v240, v240, v119
	v_max3_f32 v241, v120, v121, v122
	v_max3_f32 v241, v241, v123, v124
	v_max3_f32 v241, v241, v125, v126
	v_max_f32_e32 v241, v241, v127
	v_max_f32_e32 v240, v240, v241
	v_cmp_lt_f32_e32 vcc, 0x41c00000, v240
	s_nop 1
	s_cbranch_vccnz .Lfoxf_fb0
	s_waitcnt lgkmcnt(0)
	v_sub_f32_e32 v208, v246, v224
	v_sub_f32_e32 v209, v246, v225
	v_sub_f32_e32 v210, v246, v226
	v_sub_f32_e32 v211, v246, v227
	v_sub_f32_e32 v212, v246, v228
	v_sub_f32_e32 v213, v246, v229
	v_sub_f32_e32 v214, v246, v230
	v_sub_f32_e32 v215, v246, v231
	v_mfma_f32_16x16x32_bf16 v[208:211], v[64:67], v[96:99], v[208:211]
	v_exp_f32_e32 v112, v112
	v_exp_f32_e32 v113, v113
	v_exp_f32_e32 v114, v114
	v_exp_f32_e32 v115, v115
	v_exp_f32_e32 v116, v116
	v_sub_f32_e32 v216, v247, v224
	v_sub_f32_e32 v217, v247, v225
	v_sub_f32_e32 v218, v247, v226
	v_sub_f32_e32 v219, v247, v227
	v_mfma_f32_16x16x32_bf16 v[212:215], v[68:71], v[96:99], v[212:215]
	v_exp_f32_e32 v117, v117
	v_exp_f32_e32 v118, v118
	v_exp_f32_e32 v119, v119
	v_exp_f32_e32 v120, v120
	v_exp_f32_e32 v121, v121
	v_sub_f32_e32 v220, v247, v228
	v_sub_f32_e32 v221, v247, v229
	v_sub_f32_e32 v222, v247, v230
	v_sub_f32_e32 v223, v247, v231
	v_mfma_f32_16x16x32_bf16 v[216:219], v[64:67], v[104:107], v[216:219]
	v_exp_f32_e32 v122, v122
	v_exp_f32_e32 v123, v123
	v_exp_f32_e32 v124, v124
	v_exp_f32_e32 v125, v125
	v_exp_f32_e32 v126, v126
	v_mfma_f32_16x16x32_bf16 v[208:211], v[72:75], v[100:103], v[208:211]
	v_exp_f32_e32 v127, v127
	v_add_f32_e32 v240, v112, v113
	v_add_f32_e32 v242, v114, v115
	v_add_f32_e32 v240, v240, v242
	v_add_f32_e32 v242, v116, v117
	v_mfma_f32_16x16x32_bf16 v[220:223], v[68:71], v[104:107], v[220:223]
	v_add_f32_e32 v240, v240, v242
	v_add_f32_e32 v242, v118, v119
	v_add_f32_e32 v240, v240, v242
	v_add_f32_e32 v157, v157, v240
	v_add_f32_e32 v241, v120, v121
	v_mfma_f32_16x16x32_bf16 v[212:215], v[76:79], v[100:103], v[212:215]
	v_add_f32_e32 v243, v122, v123
	v_add_f32_e32 v241, v241, v243
	v_add_f32_e32 v243, v124, v125
	v_add_f32_e32 v241, v241, v243
	v_add_f32_e32 v243, v126, v127
	v_mfma_f32_16x16x32_bf16 v[216:219], v[72:75], v[108:111], v[216:219]
	v_add_f32_e32 v241, v241, v243
	v_add_f32_e32 v156, v156, v241
	v_cvt_pk_bf16_f32 v112, v112, v113
	v_cvt_pk_bf16_f32 v113, v114, v115
	v_cvt_pk_bf16_f32 v114, v116, v117
	v_mfma_f32_16x16x32_bf16 v[220:223], v[76:79], v[108:111], v[220:223]
	ds_read_b128 v[64:67], v248 offset:4096
	ds_read_b128 v[68:71], v248 offset:6144
	ds_read_b128 v[72:75], v249 offset:4096
	ds_read_b128 v[76:79], v249 offset:6144
	ds_read_b128 v[96:99], v191 offset:32768
	ds_read_b128 v[100:103], v192 offset:32768
	ds_read_b128 v[104:107], v191 offset:34816
	ds_read_b128 v[108:111], v192 offset:34816
	v_cvt_pk_bf16_f32 v115, v118, v119
	v_cvt_pk_bf16_f32 v120, v120, v121
	v_cvt_pk_bf16_f32 v121, v122, v123
	v_cvt_pk_bf16_f32 v122, v124, v125
	v_cvt_pk_bf16_f32 v123, v126, v127
	s_waitcnt lgkmcnt(12)
	v_mfma_f32_16x16x32_bf16 v[60:63], v[80:83], v[112:115], v[60:63]
	v_max3_f32 v240, v208, v209, v210
	v_max3_f32 v240, v240, v211, v212
	v_max3_f32 v240, v240, v213, v214
	v_max_f32_e32 v240, v240, v215
	v_max3_f32 v241, v216, v217, v218
	v_max3_f32 v241, v241, v219, v220
	v_max3_f32 v241, v241, v221, v222
	v_max_f32_e32 v241, v241, v223
	v_max_f32_e32 v240, v240, v241
	v_cmp_lt_f32_e32 vcc, 0x41c00000, v240
	s_nop 1
	s_cbranch_vccnz .Lfoxf_fb1
	v_mfma_f32_16x16x32_bf16 v[44:47], v[80:83], v[120:123], v[44:47]
	v_exp_f32_e32 v208, v208
	v_exp_f32_e32 v209, v209
	v_exp_f32_e32 v210, v210
	v_mfma_f32_16x16x32_bf16 v[56:59], v[84:87], v[112:115], v[56:59]
	v_exp_f32_e32 v211, v211
	v_exp_f32_e32 v212, v212
	v_exp_f32_e32 v213, v213
	v_mfma_f32_16x16x32_bf16 v[36:39], v[84:87], v[120:123], v[36:39]
	v_exp_f32_e32 v214, v214
	v_exp_f32_e32 v215, v215
	v_mfma_f32_16x16x32_bf16 v[52:55], v[88:91], v[112:115], v[52:55]
	v_exp_f32_e32 v216, v216
	v_exp_f32_e32 v217, v217
	v_exp_f32_e32 v218, v218
	v_mfma_f32_16x16x32_bf16 v[32:35], v[88:91], v[120:123], v[32:35]
	v_exp_f32_e32 v219, v219
	v_exp_f32_e32 v220, v220
	v_exp_f32_e32 v221, v221
	v_mfma_f32_16x16x32_bf16 v[48:51], v[92:95], v[112:115], v[48:51]
	v_exp_f32_e32 v222, v222
	v_exp_f32_e32 v223, v223
	v_mfma_f32_16x16x32_bf16 v[28:31], v[92:95], v[120:123], v[28:31]
	v_add_f32_e32 v240, v208, v209
	v_add_f32_e32 v242, v210, v211
	v_add_f32_e32 v240, v240, v242
	s_waitcnt lgkmcnt(0)
	s_waitcnt vmcnt(0)
	v_sub_f32_e32 v112, v244, v232
	v_sub_f32_e32 v113, v244, v233
	v_sub_f32_e32 v114, v244, v234
	v_sub_f32_e32 v115, v244, v235
	v_sub_f32_e32 v116, v244, v236
	v_sub_f32_e32 v117, v244, v237
	v_sub_f32_e32 v118, v244, v238
	v_sub_f32_e32 v119, v244, v239
	v_mfma_f32_16x16x32_bf16 v[112:115], v[64:67], v[96:99], v[112:115]
	v_add_f32_e32 v242, v212, v213
	v_add_f32_e32 v240, v240, v242
	v_add_f32_e32 v242, v214, v215
	v_sub_f32_e32 v120, v245, v232
	v_sub_f32_e32 v121, v245, v233
	v_sub_f32_e32 v122, v245, v234
	v_sub_f32_e32 v123, v245, v235
	v_mfma_f32_16x16x32_bf16 v[116:119], v[68:71], v[96:99], v[116:119]
	v_add_f32_e32 v240, v240, v242
	v_add_f32_e32 v151, v151, v240
	v_sub_f32_e32 v124, v245, v236
	v_sub_f32_e32 v125, v245, v237
	v_sub_f32_e32 v126, v245, v238
	v_sub_f32_e32 v127, v245, v239
	v_mfma_f32_16x16x32_bf16 v[120:123], v[64:67], v[104:107], v[120:123]
	v_add_f32_e32 v241, v216, v217
	v_add_f32_e32 v243, v218, v219
	v_add_f32_e32 v241, v241, v243
	v_mfma_f32_16x16x32_bf16 v[112:115], v[72:75], v[100:103], v[112:115]
	v_add_f32_e32 v243, v220, v221
	v_add_f32_e32 v241, v241, v243
	v_add_f32_e32 v243, v222, v223
	v_mfma_f32_16x16x32_bf16 v[124:127], v[68:71], v[104:107], v[124:127]
	v_add_f32_e32 v241, v241, v243
	v_add_f32_e32 v150, v150, v241
	v_mfma_f32_16x16x32_bf16 v[116:119], v[76:79], v[100:103], v[116:119]
	v_cvt_pk_bf16_f32 v208, v208, v209
	v_cvt_pk_bf16_f32 v209, v210, v211
	v_cvt_pk_bf16_f32 v210, v212, v213
	v_mfma_f32_16x16x32_bf16 v[120:123], v[72:75], v[108:111], v[120:123]
	v_cvt_pk_bf16_f32 v211, v214, v215
	v_cvt_pk_bf16_f32 v216, v216, v217
	v_cvt_pk_bf16_f32 v217, v218, v219
	v_mfma_f32_16x16x32_bf16 v[124:127], v[76:79], v[108:111], v[124:127]
	ds_read_b128 v[96:99], v191 offset:36864
	ds_read_b128 v[100:103], v192 offset:36864
	ds_read_b128 v[104:107], v191 offset:38912
	ds_read_b128 v[108:111], v192 offset:38912
	v_cvt_pk_bf16_f32 v218, v220, v221
	v_cvt_pk_bf16_f32 v219, v222, v223
	v_mfma_f32_16x16x32_bf16 v[40:43], v[80:83], v[208:211], v[40:43]
	v_max3_f32 v240, v112, v113, v114
	v_max3_f32 v240, v240, v115, v116
	v_max3_f32 v240, v240, v117, v118
	v_max_f32_e32 v240, v240, v119
	v_max3_f32 v241, v120, v121, v122
	v_max3_f32 v241, v241, v123, v124
	v_max3_f32 v241, v241, v125, v126
	v_max_f32_e32 v241, v241, v127
	v_max_f32_e32 v240, v240, v241
	v_cmp_lt_f32_e32 vcc, 0x41c00000, v240
	s_nop 1
	s_cbranch_vccnz .Lfoxf_fb2
	v_mfma_f32_16x16x32_bf16 v[12:15], v[80:83], v[216:219], v[12:15]
	v_exp_f32_e32 v112, v112
	v_exp_f32_e32 v113, v113
	v_exp_f32_e32 v114, v114
	v_mfma_f32_16x16x32_bf16 v[24:27], v[84:87], v[208:211], v[24:27]
	v_exp_f32_e32 v115, v115
	v_exp_f32_e32 v116, v116
	v_exp_f32_e32 v117, v117
	v_mfma_f32_16x16x32_bf16 v[8:11], v[84:87], v[216:219], v[8:11]
	v_exp_f32_e32 v118, v118
	v_exp_f32_e32 v119, v119
	v_mfma_f32_16x16x32_bf16 v[20:23], v[88:91], v[208:211], v[20:23]
	v_exp_f32_e32 v120, v120
	v_exp_f32_e32 v121, v121
	v_exp_f32_e32 v122, v122
	v_mfma_f32_16x16x32_bf16 v[0:3], v[88:91], v[216:219], v[0:3]
	v_exp_f32_e32 v123, v123
	v_exp_f32_e32 v124, v124
	v_exp_f32_e32 v125, v125
	v_mfma_f32_16x16x32_bf16 v[16:19], v[92:95], v[208:211], v[16:19]
	v_exp_f32_e32 v126, v126
	v_exp_f32_e32 v127, v127
	v_mfma_f32_16x16x32_bf16 v[4:7], v[92:95], v[216:219], v[4:7]
	v_add_f32_e32 v240, v112, v113
	v_add_f32_e32 v242, v114, v115
	v_add_f32_e32 v240, v240, v242
	ds_read_b64 v[80:81], v189 offset:8192
	ds_read_b64 v[82:83], v190 offset:8192
	ds_read_b64 v[84:85], v189 offset:10240
	ds_read_b64 v[86:87], v190 offset:10240
	ds_read_b64 v[88:89], v189 offset:12288
	ds_read_b64 v[90:91], v190 offset:12288
	ds_read_b64 v[92:93], v189 offset:14336
	ds_read_b64 v[94:95], v190 offset:14336
	s_waitcnt lgkmcnt(8)
	v_sub_f32_e32 v208, v246, v232
	v_sub_f32_e32 v209, v246, v233
	v_sub_f32_e32 v210, v246, v234
	v_sub_f32_e32 v211, v246, v235
	v_sub_f32_e32 v212, v246, v236
	v_sub_f32_e32 v213, v246, v237
	v_sub_f32_e32 v214, v246, v238
	v_sub_f32_e32 v215, v246, v239
	v_mfma_f32_16x16x32_bf16 v[208:211], v[64:67], v[96:99], v[208:211]
	v_add_f32_e32 v242, v116, v117
	v_add_f32_e32 v240, v240, v242
	v_add_f32_e32 v242, v118, v119
	v_sub_f32_e32 v216, v247, v232
	v_sub_f32_e32 v217, v247, v233
	v_sub_f32_e32 v218, v247, v234
	v_sub_f32_e32 v219, v247, v235
	v_mfma_f32_16x16x32_bf16 v[212:215], v[68:71], v[96:99], v[212:215]
	v_add_f32_e32 v240, v240, v242
	v_add_f32_e32 v157, v157, v240
	v_sub_f32_e32 v220, v247, v236
	v_sub_f32_e32 v221, v247, v237
	v_sub_f32_e32 v222, v247, v238
	v_sub_f32_e32 v223, v247, v239
	v_mfma_f32_16x16x32_bf16 v[216:219], v[64:67], v[104:107], v[216:219]
	v_add_f32_e32 v241, v120, v121
	v_add_f32_e32 v243, v122, v123
	v_add_f32_e32 v241, v241, v243
	v_mfma_f32_16x16x32_bf16 v[208:211], v[72:75], v[100:103], v[208:211]
	v_add_f32_e32 v243, v124, v125
	v_add_f32_e32 v241, v241, v243
	v_add_f32_e32 v243, v126, v127
	v_mfma_f32_16x16x32_bf16 v[220:223], v[68:71], v[104:107], v[220:223]
	v_add_f32_e32 v241, v241, v243
	v_add_f32_e32 v156, v156, v241
	v_mfma_f32_16x16x32_bf16 v[212:215], v[76:79], v[100:103], v[212:215]
	v_cvt_pk_bf16_f32 v112, v112, v113
	v_cvt_pk_bf16_f32 v113, v114, v115
	v_cvt_pk_bf16_f32 v114, v116, v117
	v_mfma_f32_16x16x32_bf16 v[216:219], v[72:75], v[108:111], v[216:219]
	v_cvt_pk_bf16_f32 v115, v118, v119
	v_cvt_pk_bf16_f32 v120, v120, v121
	v_cvt_pk_bf16_f32 v121, v122, v123
	v_mfma_f32_16x16x32_bf16 v[220:223], v[76:79], v[108:111], v[220:223]
	v_cvt_pk_bf16_f32 v122, v124, v125
	v_cvt_pk_bf16_f32 v123, v126, v127
	s_waitcnt lgkmcnt(0)
	v_mfma_f32_16x16x32_bf16 v[60:63], v[80:83], v[112:115], v[60:63]
	v_max3_f32 v240, v208, v209, v210
	v_max3_f32 v240, v240, v211, v212
	v_max3_f32 v240, v240, v213, v214
	v_max_f32_e32 v240, v240, v215
	v_max3_f32 v241, v216, v217, v218
	v_max3_f32 v241, v241, v219, v220
	v_max3_f32 v241, v241, v221, v222
	v_max_f32_e32 v241, v241, v223
	v_max_f32_e32 v240, v240, v241
	v_cmp_lt_f32_e32 vcc, 0x41c00000, v240
	s_nop 1
	s_cbranch_vccnz .Lfoxf_fb3
	v_mfma_f32_16x16x32_bf16 v[44:47], v[80:83], v[120:123], v[44:47]
	v_exp_f32_e32 v208, v208
	v_exp_f32_e32 v209, v209
	v_exp_f32_e32 v210, v210
	v_exp_f32_e32 v211, v211
	v_exp_f32_e32 v212, v212
	v_exp_f32_e32 v213, v213
	v_mfma_f32_16x16x32_bf16 v[56:59], v[84:87], v[112:115], v[56:59]
	v_exp_f32_e32 v214, v214
	v_exp_f32_e32 v215, v215
	v_exp_f32_e32 v216, v216
	v_exp_f32_e32 v217, v217
	v_exp_f32_e32 v218, v218
	v_exp_f32_e32 v219, v219
	v_mfma_f32_16x16x32_bf16 v[36:39], v[84:87], v[120:123], v[36:39]
	v_exp_f32_e32 v220, v220
	v_exp_f32_e32 v221, v221
	v_exp_f32_e32 v222, v222
	v_exp_f32_e32 v223, v223
	v_add_f32_e32 v240, v208, v209
	v_add_f32_e32 v242, v210, v211
	v_mfma_f32_16x16x32_bf16 v[52:55], v[88:91], v[112:115], v[52:55]
	v_add_f32_e32 v240, v240, v242
	v_add_f32_e32 v242, v212, v213
	v_add_f32_e32 v240, v240, v242
	v_add_f32_e32 v242, v214, v215
	v_add_f32_e32 v240, v240, v242
	v_mfma_f32_16x16x32_bf16 v[32:35], v[88:91], v[120:123], v[32:35]
	v_add_f32_e32 v151, v151, v240
	v_add_f32_e32 v241, v216, v217
	v_add_f32_e32 v243, v218, v219
	v_add_f32_e32 v241, v241, v243
	v_add_f32_e32 v243, v220, v221
	v_add_f32_e32 v241, v241, v243
	v_mfma_f32_16x16x32_bf16 v[48:51], v[92:95], v[112:115], v[48:51]
	v_add_f32_e32 v243, v222, v223
	v_add_f32_e32 v241, v241, v243
	v_add_f32_e32 v150, v150, v241
	v_cvt_pk_bf16_f32 v208, v208, v209
	v_cvt_pk_bf16_f32 v209, v210, v211
	v_cvt_pk_bf16_f32 v210, v212, v213
	v_mfma_f32_16x16x32_bf16 v[28:31], v[92:95], v[120:123], v[28:31]
	v_cvt_pk_bf16_f32 v211, v214, v215
	v_cvt_pk_bf16_f32 v216, v216, v217
	v_cvt_pk_bf16_f32 v217, v218, v219
	v_cvt_pk_bf16_f32 v218, v220, v221
	v_cvt_pk_bf16_f32 v219, v222, v223
	s_nop 1
	v_mfma_f32_16x16x32_bf16 v[40:43], v[80:83], v[208:211], v[40:43]
	v_mfma_f32_16x16x32_bf16 v[12:15], v[80:83], v[216:219], v[12:15]
	v_mfma_f32_16x16x32_bf16 v[24:27], v[84:87], v[208:211], v[24:27]
	v_mfma_f32_16x16x32_bf16 v[8:11], v[84:87], v[216:219], v[8:11]
	v_mfma_f32_16x16x32_bf16 v[20:23], v[88:91], v[208:211], v[20:23]
	v_mfma_f32_16x16x32_bf16 v[0:3], v[88:91], v[216:219], v[0:3]
	v_mfma_f32_16x16x32_bf16 v[16:19], v[92:95], v[208:211], v[16:19]
	v_mfma_f32_16x16x32_bf16 v[4:7], v[92:95], v[216:219], v[4:7]
	s_branch .LBB0_65
